# P3 epilogue: second-half operand loads issued together with the first half's (one burst, spare VGPRs), second-half waits removed; on top of packed P4 epilogue
# baseline (speedup 1.0000x reference)
; __device__ __forceinline__ unsigned cvt_pk_bf16(float lo, float hi) { unsigned r; asm volatile("v_cvt_pk_bf16_f32 %0, %1, %2" : "=v"(r) : "v"(lo), "v"(hi)); return r; }
; __host__ __device__ __forceinline__ size_t blk_off(int row, int col, int K) { return ((size_t)(row >> 8) * (K >> 6) + (col >> 6)) * (256 * 64) + (size_t)(row & 255) * 64 + (col & 63); }
;     __device__ __forceinline__ void operator()(const f32x4 (&acc)[2][2][4][2], const Unit& u, int wr, int wc, int fr, int fq) const {
;         const int row0 = u.pm * BM + wr * 64 + fr, col0 = u.pn * BM + wc * 32 + 8 * fq;
; #pragma unroll
;         for (int ai = 0; ai < 2; ++ai) {
;             u32x4 xw[4][2]; float rq[4];
; #pragma unroll
;             for (int m = 0; m < 4; ++m) { const int row = row0 + ai * HALF + m * 16; rq[m] = rmsx[row];
; #pragma unroll
;                 for (int bj = 0; bj < 2; ++bj) xw[m][bj] = __builtin_nontemporal_load((const u32x4*)(xn + (size_t)row * 1024 + col0 + bj * HALF)); }
;             asm volatile("" ::: "memory");
; #pragma unroll
;             for (int m = 0; m < 4; ++m) { const int row = row0 + ai * HALF + m * 16; const size_t off = (size_t)row * 1024 + col0; float ss = 0.f; const float q = rq[m];
; #pragma unroll
;                 for (int bj = 0; bj < 2; ++bj) { const u32x4 w = xw[m][bj];
;                     const f32x4 x0 = (f32x4){__builtin_bit_cast(float, w.x << 16), __builtin_bit_cast(float, w.x & 0xffff0000u), __builtin_bit_cast(float, w.y << 16), __builtin_bit_cast(float, w.y & 0xffff0000u)};
;                     const f32x4 x1 = (f32x4){__builtin_bit_cast(float, w.z << 16), __builtin_bit_cast(float, w.z & 0xffff0000u), __builtin_bit_cast(float, w.w << 16), __builtin_bit_cast(float, w.w & 0xffff0000u)};
;                     const f32x4 v0 = x0 * q + acc[ai][bj][m][0], v1 = x1 * q + acc[ai][bj][m][1];
;                     ss += (v0[0] * v0[0] + v0[1] * v0[1]) + (v0[2] * v0[2] + v0[3] * v0[3]) + (v1[0] * v1[0] + v1[1] * v1[1]) + (v1[2] * v1[2] + v1[3] * v1[3]);
;                     u32x4 o; o.x = cvt_pk_bf16(v0[0], v0[1]); o.y = cvt_pk_bf16(v0[2], v0[3]); o.z = cvt_pk_bf16(v1[0], v1[1]); o.w = cvt_pk_bf16(v1[2], v1[3]);
;                     *(u32x4*)(x1b + blk_off(row, col0 + bj * HALF, 1024)) = o; }
;                 ss += __shfl_xor(ss, 16); ss += __shfl_xor(ss, 32);
;                 if (fq == 0) part[(size_t)row * 16 + u.pn * 4 + wc] = ss; }
.LBB0_486:
	s_lshl_b32 s2, s14, 8
	s_add_i32 s16, s16, s60
	s_or_b32 s2, s2, s61
	v_or_b32_e32 v168, s16, v183
	v_or_b32_e32 v2, s2, v185
	v_ashrrev_i32_e32 v3, 31, v2
	v_ashrrev_i32_e32 v169, 31, v168
	v_lshl_add_u64 v[2:3], v[2:3], 1, s[62:63]
	v_lshlrev_b64 v[132:133], 11, v[168:169]
	v_lshl_add_u64 v[132:133], v[2:3], 0, v[132:133]
	v_lshl_add_u64 v[170:171], v[168:169], 2, s[20:21]
	global_load_dwordx4 v[190:193], v[132:133], off nt
	global_load_dwordx4 v[194:197], v[132:133], off offset:256 nt
	global_load_dword v198, v[170:171], off
	v_or_b32_e32 v180, 16, v168
	v_or_b32_e32 v176, 32, v168
	v_or_b32_e32 v172, 48, v168
	v_ashrrev_i32_e32 v181, 31, v180
	v_ashrrev_i32_e32 v177, 31, v176
	v_lshlrev_b32_e32 v132, 7, v168
	v_ashrrev_i32_e32 v173, 31, v172
	v_lshlrev_b64 v[134:135], 11, v[180:181]
	v_lshlrev_b64 v[138:139], 11, v[176:177]
	v_and_b32_e32 v200, 0x6780, v132
	v_lshl_add_u64 v[132:133], v[180:181], 2, s[20:21]
	v_lshl_add_u64 v[136:137], v[176:177], 2, s[20:21]
	v_lshlrev_b64 v[140:141], 11, v[172:173]
	v_lshl_add_u64 v[134:135], v[2:3], 0, v[134:135]
	v_lshl_add_u64 v[138:139], v[2:3], 0, v[138:139]
	v_lshl_add_u64 v[202:203], v[172:173], 2, s[20:21]
	v_lshl_add_u64 v[204:205], v[2:3], 0, v[140:141]
	global_load_dword v182, v[132:133], off
	global_load_dwordx4 v[152:155], v[134:135], off nt
	global_load_dwordx4 v[148:151], v[134:135], off offset:256 nt
	global_load_dword v178, v[136:137], off
	global_load_dwordx4 v[144:147], v[138:139], off nt
	global_load_dwordx4 v[140:143], v[138:139], off offset:256 nt
	global_load_dword v174, v[202:203], off
	s_nop 0
	global_load_dwordx4 v[136:139], v[204:205], off nt
	global_load_dwordx4 v[132:135], v[204:205], off offset:256 nt
	v_add_u32_e32 v250, 0x80, v168
	v_ashrrev_i32_e32 v251, 31, v250
	v_lshlrev_b64 v[250:251], 11, v[250:251]
	v_lshl_add_u64 v[250:251], v[2:3], 0, v[250:251]
	global_load_dwordx4 v[212:215], v[250:251], off nt
	global_load_dwordx4 v[216:219], v[250:251], off offset:256 nt
	v_add_u32_e32 v250, 0x90, v168
	v_ashrrev_i32_e32 v251, 31, v250
	v_lshlrev_b64 v[250:251], 11, v[250:251]
	v_lshl_add_u64 v[250:251], v[2:3], 0, v[250:251]
	global_load_dwordx4 v[220:223], v[250:251], off nt
	global_load_dwordx4 v[224:227], v[250:251], off offset:256 nt
	v_add_u32_e32 v250, 0xa0, v168
	v_ashrrev_i32_e32 v251, 31, v250
	v_lshlrev_b64 v[250:251], 11, v[250:251]
	v_lshl_add_u64 v[250:251], v[2:3], 0, v[250:251]
	global_load_dwordx4 v[228:231], v[250:251], off nt
	global_load_dwordx4 v[232:235], v[250:251], off offset:256 nt
	v_add_u32_e32 v250, 0xb0, v168
	v_ashrrev_i32_e32 v251, 31, v250
	v_lshlrev_b64 v[250:251], 11, v[250:251]
	v_lshl_add_u64 v[250:251], v[2:3], 0, v[250:251]
	global_load_dwordx4 v[236:239], v[250:251], off nt
	global_load_dwordx4 v[240:243], v[250:251], off offset:256 nt
	global_load_dword v246, v[170:171], off offset:512
	global_load_dword v248, v[170:171], off offset:576
	global_load_dword v252, v[170:171], off offset:640
	global_load_dword v254, v[170:171], off offset:704
	s_ashr_i32 s38, s16, 8
	s_ashr_i32 s40, s2, 6
	s_ashr_i32 s39, s38, 31
	s_ashr_i32 s41, s40, 31
	s_lshl_b64 s[44:45], s[38:39], 19
	s_lshl_b64 s[38:39], s[40:41], 15
	s_add_u32 s38, s10, s38
	s_addc_u32 s39, s11, s39
	s_add_u32 s42, s38, s44
	v_mov_b32_e32 v201, v1
	v_bitop3_b32 v0, s2, 56, v185 bitop3:0xc8
	s_addc_u32 s43, s39, s45
	v_lshlrev_b32_e32 v0, 1, v0
	v_lshl_add_u64 v[202:203], s[42:43], 0, v[200:201]
	v_lshl_add_u64 v[202:203], v[202:203], 0, v[0:1]
	s_or_b32 s40, s40, 2
	s_ashr_i32 s41, s40, 31
	s_lshl_b64 s[40:41], s[40:41], 15
	s_add_u32 s40, s10, s40
	s_addc_u32 s41, s11, s41
	s_add_u32 s44, s40, s44
	s_addc_u32 s45, s41, s45
	s_waitcnt vmcnt(0)
	v_lshlrev_b32_e32 v206, 16, v192
	v_and_b32_e32 v207, 0xffff0000, v192
	v_lshlrev_b32_e32 v192, 16, v193
	v_and_b32_e32 v193, 0xffff0000, v193
	v_lshlrev_b32_e32 v204, 16, v190
	v_and_b32_e32 v205, 0xffff0000, v190
	v_lshlrev_b32_e32 v190, 16, v191
	v_and_b32_e32 v191, 0xffff0000, v191
	v_lshlrev_b32_e32 v208, 16, v194
	v_and_b32_e32 v209, 0xffff0000, v194
	v_lshlrev_b32_e32 v194, 16, v195
	v_and_b32_e32 v195, 0xffff0000, v195
	v_pk_fma_f32 v[126:127], v[198:199], v[192:193], v[126:127] op_sel_hi:[0,1,1]
	v_pk_fma_f32 v[130:131], v[198:199], v[190:191], v[130:131] op_sel_hi:[0,1,1]
	v_pk_fma_f32 v[128:129], v[198:199], v[204:205], v[128:129] op_sel_hi:[0,1,1]
	v_pk_fma_f32 v[190:191], v[198:199], v[206:207], v[124:125] op_sel_hi:[0,1,1]
	v_pk_fma_f32 v[192:193], v[198:199], v[194:195], v[122:123] op_sel_hi:[0,1,1]
	v_mul_f32_e32 v199, v127, v127
	v_fmac_f32_e32 v199, v126, v126
	v_cvt_pk_bf16_f32 v122, v128, v129
	v_cvt_pk_bf16_f32 v123, v130, v131
	v_cvt_pk_bf16_f32 v124, v190, v191
	v_pk_fma_f32 v[120:121], v[198:199], v[208:209], v[120:121] op_sel_hi:[0,1,1]
	v_lshlrev_b32_e32 v210, 16, v196
	v_and_b32_e32 v211, 0xffff0000, v196
	v_cvt_pk_bf16_f32 v125, v126, v127
	global_store_dwordx4 v[202:203], v[122:125], off
	v_pk_fma_f32 v[116:117], v[198:199], v[210:211], v[116:117] op_sel_hi:[0,1,1]
	v_lshlrev_b32_e32 v196, 16, v197
	v_mul_f32_e32 v123, v121, v121
	v_mul_f32_e32 v124, v193, v193
	v_fmac_f32_e32 v123, v120, v120
	v_fmac_f32_e32 v124, v192, v192
	v_and_b32_e32 v197, 0xffff0000, v197
	v_mul_f32_e32 v189, v129, v129
	v_mul_f32_e32 v194, v131, v131
	v_add_f32_e32 v123, v123, v124
	v_mul_f32_e32 v124, v117, v117
	v_mul_f32_e32 v195, v191, v191
	v_fmac_f32_e32 v189, v128, v128
	v_fmac_f32_e32 v194, v130, v130
	v_pk_fma_f32 v[118:119], v[198:199], v[196:197], v[118:119] op_sel_hi:[0,1,1]
	v_fmac_f32_e32 v124, v116, v116
	v_fmac_f32_e32 v195, v190, v190
	v_add_f32_e32 v122, v189, v194
	v_add_f32_e32 v123, v124, v123
	v_mul_f32_e32 v124, v119, v119
	v_add_f32_e32 v122, v195, v122
	v_fmac_f32_e32 v124, v118, v118
	v_add_f32_e32 v122, v199, v122
	v_add_f32_e32 v123, v124, v123
	v_add_f32_e32 v124, v122, v123
	v_cvt_pk_bf16_f32 v120, v120, v121
	v_cvt_pk_bf16_f32 v121, v192, v193
	v_cvt_pk_bf16_f32 v122, v116, v117
	v_and_b32_e32 v117, 64, v188
	v_xor_b32_e32 v116, 16, v188
	v_add_u32_e32 v117, 64, v117
	v_cmp_lt_i32_e32 vcc, v116, v117
	v_cvt_pk_bf16_f32 v123, v118, v119
	v_xor_b32_e32 v119, 32, v188
	s_nop 0
	v_cndmask_b32_e32 v116, v188, v116, vcc
	v_lshlrev_b32_e32 v116, 2, v116
	ds_bpermute_b32 v118, v116, v124
	v_cmp_lt_i32_e32 vcc, v119, v117
	s_waitcnt lgkmcnt(0)
	v_add_f32_e32 v118, v124, v118
	v_cndmask_b32_e32 v117, v188, v119, vcc
	v_lshlrev_b32_e32 v117, 2, v117
	ds_bpermute_b32 v119, v117, v118
	v_lshl_add_u64 v[124:125], s[44:45], 0, v[200:201]
	v_lshl_add_u64 v[124:125], v[124:125], 0, v[0:1]
	global_store_dwordx4 v[124:125], v[120:123], off
	s_and_saveexec_b64 s[48:49], s[6:7]
	s_cbranch_execz .LBB0_488
	s_waitcnt lgkmcnt(0)
	v_add_f32_e32 v120, v118, v119
	s_lshl_b32 s74, s14, 2
	v_lshlrev_b64 v[118:119], 6, v[168:169]
	s_ashr_i32 s75, s74, 31
	v_lshl_add_u64 v[118:119], s[8:9], 0, v[118:119]
	v_lshl_add_u64 v[118:119], s[74:75], 2, v[118:119]
	s_lshl_b32 s16, s59, 2
	v_lshl_add_u64 v[118:119], v[118:119], 0, s[16:17]
	global_store_dword v[118:119], v120, off

; __device__ __forceinline__ unsigned cvt_pk_bf16(float lo, float hi) { unsigned r; asm volatile("v_cvt_pk_bf16_f32 %0, %1, %2" : "=v"(r) : "v"(lo), "v"(hi)); return r; }
; __host__ __device__ __forceinline__ size_t blk_off(int row, int col, int K) { return ((size_t)(row >> 8) * (K >> 6) + (col >> 6)) * (256 * 64) + (size_t)(row & 255) * 64 + (col & 63); }
;     __device__ __forceinline__ void operator()(const f32x4 (&acc)[2][2][4][2], const Unit& u, int wr, int wc, int fr, int fq) const {
;     ...
;             for (int m = 0; m < 4; ++m) { const int row = row0 + ai * HALF + m * 16; rq[m] = rmsx[row];
; #pragma unroll
;                 for (int bj = 0; bj < 2; ++bj) xw[m][bj] = __builtin_nontemporal_load((const u32x4*)(xn + (size_t)row * 1024 + col0 + bj * HALF)); }
;             asm volatile("" ::: "memory");
; #pragma unroll
;             for (int m = 0; m < 4; ++m) { const int row = row0 + ai * HALF + m * 16; const size_t off = (size_t)row * 1024 + col0; float ss = 0.f; const float q = rq[m];
; #pragma unroll
;                 for (int bj = 0; bj < 2; ++bj) { const u32x4 w = xw[m][bj];
;                     const f32x4 x0 = (f32x4){__builtin_bit_cast(float, w.x << 16), __builtin_bit_cast(float, w.x & 0xffff0000u), __builtin_bit_cast(float, w.y << 16), __builtin_bit_cast(float, w.y & 0xffff0000u)};
;                     const f32x4 x1 = (f32x4){__builtin_bit_cast(float, w.z << 16), __builtin_bit_cast(float, w.z & 0xffff0000u), __builtin_bit_cast(float, w.w << 16), __builtin_bit_cast(float, w.w & 0xffff0000u)};
;                     const f32x4 v0 = x0 * q + acc[ai][bj][m][0], v1 = x1 * q + acc[ai][bj][m][1];
;                     ss += (v0[0] * v0[0] + v0[1] * v0[1]) + (v0[2] * v0[2] + v0[3] * v0[3]) + (v1[0] * v1[0] + v1[1] * v1[1]) + (v1[2] * v1[2] + v1[3] * v1[3]);
;                     u32x4 o; o.x = cvt_pk_bf16(v0[0], v0[1]); o.y = cvt_pk_bf16(v0[2], v0[3]); o.z = cvt_pk_bf16(v1[0], v1[1]); o.w = cvt_pk_bf16(v1[2], v1[3]);
;                     *(u32x4*)(x1b + blk_off(row, col0 + bj * HALF, 1024)) = o; }
;                 ss += __shfl_xor(ss, 16); ss += __shfl_xor(ss, 32);
;                 if (fq == 0) part[(size_t)row * 16 + u.pn * 4 + wc] = ss; }
.LBB0_494:
	s_or_b64 exec, exec, s[42:43]
	v_add_u32_e32 v104, 0x80, v168
	v_ashrrev_i32_e32 v105, 31, v104
	s_waitcnt lgkmcnt(0)
	v_lshlrev_b64 v[68:69], 11, v[104:105]
	v_lshl_add_u64 v[68:69], v[2:3], 0, v[68:69]
	v_add_u32_e32 v100, 0x90, v168
	v_add_u32_e32 v96, 0xa0, v168
	v_add_u32_e32 v92, 0xb0, v168
	v_ashrrev_i32_e32 v101, 31, v100
	v_ashrrev_i32_e32 v97, 31, v96
	v_ashrrev_i32_e32 v93, 31, v92
	v_lshlrev_b64 v[68:69], 11, v[100:101]
	v_lshlrev_b64 v[70:71], 11, v[96:97]
	v_lshlrev_b64 v[72:73], 11, v[92:93]
	v_lshl_add_u64 v[68:69], v[2:3], 0, v[68:69]
	v_lshl_add_u64 v[70:71], v[2:3], 0, v[70:71]
	v_lshl_add_u64 v[2:3], v[2:3], 0, v[72:73]
	s_nop 0
	v_ashrrev_i32_e32 v2, 8, v104
	v_ashrrev_i32_e32 v3, 31, v2
	v_lshlrev_b32_e32 v95, 7, v104
	v_lshlrev_b64 v[120:121], 19, v[2:3]
	v_mov_b32_e32 v119, v1
	v_and_b32_e32 v118, 0x6780, v95
	v_lshl_add_u64 v[2:3], s[38:39], 0, v[120:121]
	v_lshl_add_u64 v[122:123], v[2:3], 0, v[118:119]
	v_lshl_add_u64 v[122:123], v[122:123], 0, v[0:1]
	v_lshlrev_b32_e32 v124, 16, v212
	v_and_b32_e32 v125, 0xffff0000, v212
	v_lshlrev_b32_e32 v106, 16, v213
	v_and_b32_e32 v107, 0xffff0000, v213
	v_lshlrev_b32_e32 v126, 16, v214
	v_and_b32_e32 v127, 0xffff0000, v214
	v_lshlrev_b32_e32 v108, 16, v215
	v_and_b32_e32 v109, 0xffff0000, v215
	v_lshlrev_b32_e32 v128, 16, v216
	v_and_b32_e32 v129, 0xffff0000, v216
	v_lshlrev_b32_e32 v110, 16, v217
	v_and_b32_e32 v111, 0xffff0000, v217
	v_lshlrev_b32_e32 v130, 16, v218
	v_and_b32_e32 v131, 0xffff0000, v218
	v_lshlrev_b32_e32 v112, 16, v219
	v_and_b32_e32 v113, 0xffff0000, v219
	v_pk_fma_f32 v[66:67], v[246:247], v[106:107], v[66:67] op_sel_hi:[0,1,1]
	v_pk_fma_f32 v[64:65], v[246:247], v[124:125], v[64:65] op_sel_hi:[0,1,1]
	v_pk_fma_f32 v[62:63], v[246:247], v[108:109], v[62:63] op_sel_hi:[0,1,1]
	v_pk_fma_f32 v[60:61], v[246:247], v[126:127], v[60:61] op_sel_hi:[0,1,1]
	v_pk_fma_f32 v[58:59], v[246:247], v[110:111], v[58:59] op_sel_hi:[0,1,1]
	v_pk_fma_f32 v[56:57], v[246:247], v[128:129], v[56:57] op_sel_hi:[0,1,1]
	v_pk_fma_f32 v[106:107], v[246:247], v[112:113], v[54:55] op_sel_hi:[0,1,1]
	v_pk_fma_f32 v[108:109], v[246:247], v[130:131], v[52:53] op_sel_hi:[0,1,1]
	v_mul_f32_e32 v95, v65, v65
	v_mul_f32_e32 v99, v67, v67
	v_mul_f32_e32 v103, v61, v61
	v_mul_f32_e32 v110, v63, v63
	v_cvt_pk_bf16_f32 v52, v64, v65
	v_cvt_pk_bf16_f32 v53, v66, v67
	v_cvt_pk_bf16_f32 v54, v60, v61
	v_cvt_pk_bf16_f32 v55, v62, v63
	v_mul_f32_e32 v61, v57, v57
	v_mul_f32_e32 v63, v59, v59
	v_mul_f32_e32 v65, v109, v109
	v_fmac_f32_e32 v95, v64, v64
	v_fmac_f32_e32 v99, v66, v66
	v_fmac_f32_e32 v61, v56, v56
	v_fmac_f32_e32 v63, v58, v58
	v_mul_f32_e32 v67, v107, v107
	v_fmac_f32_e32 v103, v60, v60
	global_store_dwordx4 v[122:123], v[52:55], off
	v_fmac_f32_e32 v65, v108, v108
	v_fmac_f32_e32 v110, v62, v62
	v_add_f32_e32 v52, v95, v99
	v_add_f32_e32 v53, v61, v63
	v_fmac_f32_e32 v67, v106, v106
	v_add_f32_e32 v52, v103, v52
	v_add_f32_e32 v53, v65, v53
	v_add_f32_e32 v52, v110, v52
	v_add_f32_e32 v53, v67, v53
	v_add_f32_e32 v52, v52, v53
	ds_bpermute_b32 v53, v116, v52
	v_cvt_pk_bf16_f32 v56, v56, v57
	v_cvt_pk_bf16_f32 v57, v58, v59
	v_cvt_pk_bf16_f32 v58, v108, v109
	v_cvt_pk_bf16_f32 v59, v106, v107
	s_waitcnt lgkmcnt(0)
	v_add_f32_e32 v54, v52, v53
	ds_bpermute_b32 v55, v117, v54
	v_lshl_add_u64 v[52:53], s[40:41], 0, v[120:121]
	v_lshl_add_u64 v[60:61], v[52:53], 0, v[118:119]
	v_lshl_add_u64 v[60:61], v[60:61], 0, v[0:1]
	global_store_dwordx4 v[60:61], v[56:59], off
	s_and_saveexec_b64 s[38:39], s[6:7]
	s_cbranch_execz .LBB0_496
	s_waitcnt lgkmcnt(0)
	v_add_f32_e32 v56, v54, v55
	s_lshl_b32 s40, s14, 2
	v_lshlrev_b64 v[54:55], 6, v[104:105]
	s_ashr_i32 s41, s40, 31
	v_lshl_add_u64 v[54:55], s[8:9], 0, v[54:55]
	v_lshl_add_u64 v[54:55], s[40:41], 2, v[54:55]
	s_lshl_b32 s16, s59, 2
	v_lshl_add_u64 v[54:55], v[54:55], 0, s[16:17]
	global_store_dword v[54:55], v56, off
.LBB0_496:
	s_or_b64 exec, exec, s[38:39]
	v_lshlrev_b32_e32 v54, 16, v220
	s_waitcnt lgkmcnt(0)
	v_and_b32_e32 v55, 0xffff0000, v220
	v_lshlrev_b32_e32 v56, 16, v221
	v_and_b32_e32 v57, 0xffff0000, v221
	v_lshlrev_b32_e32 v58, 16, v222
	v_and_b32_e32 v59, 0xffff0000, v222
	v_lshlrev_b32_e32 v60, 16, v223
	v_and_b32_e32 v61, 0xffff0000, v223
	v_pk_fma_f32 v[50:51], v[248:249], v[56:57], v[50:51] op_sel_hi:[0,1,1]
	v_pk_fma_f32 v[48:49], v[248:249], v[54:55], v[48:49] op_sel_hi:[0,1,1]
	v_pk_fma_f32 v[54:55], v[248:249], v[60:61], v[46:47] op_sel_hi:[0,1,1]
	v_pk_fma_f32 v[46:47], v[248:249], v[58:59], v[44:45] op_sel_hi:[0,1,1]
	v_mul_f32_e32 v44, v49, v49
	v_mul_f32_e32 v45, v51, v51
	v_fmac_f32_e32 v44, v48, v48
	v_fmac_f32_e32 v45, v50, v50
	v_add_f32_e32 v44, v44, v45
	v_mul_f32_e32 v45, v47, v47
	v_fmac_f32_e32 v45, v46, v46
	v_add_f32_e32 v44, v45, v44
	v_mul_f32_e32 v45, v55, v55
	v_fmac_f32_e32 v45, v54, v54
	v_add_f32_e32 v62, v45, v44
	v_cvt_pk_bf16_f32 v44, v48, v49
	v_cvt_pk_bf16_f32 v45, v50, v51
	v_cvt_pk_bf16_f32 v46, v46, v47
	v_cvt_pk_bf16_f32 v47, v54, v55
	v_lshlrev_b32_e32 v54, 16, v224
	v_and_b32_e32 v55, 0xffff0000, v224
	v_lshlrev_b32_e32 v56, 16, v225
	v_and_b32_e32 v57, 0xffff0000, v225
	v_lshlrev_b32_e32 v60, 16, v227
	v_and_b32_e32 v61, 0xffff0000, v227
	v_pk_fma_f32 v[42:43], v[248:249], v[56:57], v[42:43] op_sel_hi:[0,1,1]
	v_pk_fma_f32 v[40:41], v[248:249], v[54:55], v[40:41] op_sel_hi:[0,1,1]
	v_lshlrev_b32_e32 v58, 16, v226
	v_and_b32_e32 v59, 0xffff0000, v226
	v_pk_fma_f32 v[54:55], v[248:249], v[60:61], v[38:39] op_sel_hi:[0,1,1]
	v_mul_f32_e32 v38, v41, v41
	v_mul_f32_e32 v39, v43, v43
	v_pk_fma_f32 v[36:37], v[248:249], v[58:59], v[36:37] op_sel_hi:[0,1,1]
	v_fmac_f32_e32 v38, v40, v40
	v_fmac_f32_e32 v39, v42, v42
	v_add_f32_e32 v38, v38, v39
	v_mul_f32_e32 v39, v37, v37
	v_fmac_f32_e32 v39, v36, v36
	v_add_f32_e32 v38, v39, v38
	v_mul_f32_e32 v39, v55, v55
	v_fmac_f32_e32 v39, v54, v54
	v_add_f32_e32 v38, v39, v38
	v_add_f32_e32 v56, v62, v38
	ds_bpermute_b32 v57, v116, v56
	v_lshlrev_b32_e32 v48, 7, v100
	v_and_b32_e32 v48, 0x6f80, v48
	v_mov_b32_e32 v49, v1
	v_lshl_add_u64 v[50:51], v[2:3], 0, v[48:49]
	v_lshl_add_u64 v[50:51], v[50:51], 0, v[0:1]
	global_store_dwordx4 v[50:51], v[44:47], off
	v_cvt_pk_bf16_f32 v38, v40, v41
	v_cvt_pk_bf16_f32 v39, v42, v43
	v_cvt_pk_bf16_f32 v40, v36, v37
	s_waitcnt lgkmcnt(0)
	v_add_f32_e32 v36, v56, v57
	ds_bpermute_b32 v37, v117, v36
	v_lshl_add_u64 v[42:43], v[52:53], 0, v[48:49]
	v_lshl_add_u64 v[42:43], v[42:43], 0, v[0:1]
	v_cvt_pk_bf16_f32 v41, v54, v55
	global_store_dwordx4 v[42:43], v[38:41], off
	s_and_saveexec_b64 s[38:39], s[6:7]
	s_cbranch_execz .LBB0_498
	s_waitcnt lgkmcnt(0)
	v_add_f32_e32 v38, v36, v37
	s_lshl_b32 s40, s14, 2
	v_lshlrev_b64 v[36:37], 6, v[100:101]
	s_ashr_i32 s41, s40, 31
	v_lshl_add_u64 v[36:37], s[8:9], 0, v[36:37]
	v_lshl_add_u64 v[36:37], s[40:41], 2, v[36:37]
	s_lshl_b32 s16, s59, 2
	v_lshl_add_u64 v[36:37], v[36:37], 0, s[16:17]
	global_store_dword v[36:37], v38, off
; __device__ __forceinline__ unsigned cvt_pk_bf16(float lo, float hi) { unsigned r; asm volatile("v_cvt_pk_bf16_f32 %0, %1, %2" : "=v"(r) : "v"(lo), "v"(hi)); return r; }
; __host__ __device__ __forceinline__ size_t blk_off(int row, int col, int K) { return ((size_t)(row >> 8) * (K >> 6) + (col >> 6)) * (256 * 64) + (size_t)(row & 255) * 64 + (col & 63); }
;     __device__ __forceinline__ void operator()(const f32x4 (&acc)[2][2][4][2], const Unit& u, int wr, int wc, int fr, int fq) const {
;     ...
;             for (int m = 0; m < 4; ++m) { const int row = row0 + ai * HALF + m * 16; rq[m] = rmsx[row];
; #pragma unroll
;                 for (int bj = 0; bj < 2; ++bj) xw[m][bj] = __builtin_nontemporal_load((const u32x4*)(xn + (size_t)row * 1024 + col0 + bj * HALF)); }
;             asm volatile("" ::: "memory");
; #pragma unroll
;             for (int m = 0; m < 4; ++m) { const int row = row0 + ai * HALF + m * 16; const size_t off = (size_t)row * 1024 + col0; float ss = 0.f; const float q = rq[m];
; #pragma unroll
;                 for (int bj = 0; bj < 2; ++bj) { const u32x4 w = xw[m][bj];
;                     const f32x4 x0 = (f32x4){__builtin_bit_cast(float, w.x << 16), __builtin_bit_cast(float, w.x & 0xffff0000u), __builtin_bit_cast(float, w.y << 16), __builtin_bit_cast(float, w.y & 0xffff0000u)};
;                     const f32x4 x1 = (f32x4){__builtin_bit_cast(float, w.z << 16), __builtin_bit_cast(float, w.z & 0xffff0000u), __builtin_bit_cast(float, w.w << 16), __builtin_bit_cast(float, w.w & 0xffff0000u)};
;                     const f32x4 v0 = x0 * q + acc[ai][bj][m][0], v1 = x1 * q + acc[ai][bj][m][1];
;                     ss += (v0[0] * v0[0] + v0[1] * v0[1]) + (v0[2] * v0[2] + v0[3] * v0[3]) + (v1[0] * v1[0] + v1[1] * v1[1]) + (v1[2] * v1[2] + v1[3] * v1[3]);
;                     u32x4 o; o.x = cvt_pk_bf16(v0[0], v0[1]); o.y = cvt_pk_bf16(v0[2], v0[3]); o.z = cvt_pk_bf16(v1[0], v1[1]); o.w = cvt_pk_bf16(v1[2], v1[3]);
;                     *(u32x4*)(x1b + blk_off(row, col0 + bj * HALF, 1024)) = o; }
;                 ss += __shfl_xor(ss, 16); ss += __shfl_xor(ss, 32);
;                 if (fq == 0) part[(size_t)row * 16 + u.pn * 4 + wc] = ss; }
.LBB0_498:
	s_or_b64 exec, exec, s[38:39]
	v_lshlrev_b32_e32 v36, 16, v228
	s_waitcnt lgkmcnt(0)
	v_and_b32_e32 v37, 0xffff0000, v228
	v_lshlrev_b32_e32 v38, 16, v229
	v_and_b32_e32 v39, 0xffff0000, v229
	v_lshlrev_b32_e32 v40, 16, v230
	v_and_b32_e32 v41, 0xffff0000, v230
	v_lshlrev_b32_e32 v42, 16, v231
	v_and_b32_e32 v43, 0xffff0000, v231
	v_pk_fma_f32 v[34:35], v[252:253], v[38:39], v[34:35] op_sel_hi:[0,1,1]
	v_pk_fma_f32 v[32:33], v[252:253], v[36:37], v[32:33] op_sel_hi:[0,1,1]
	v_pk_fma_f32 v[36:37], v[252:253], v[42:43], v[30:31] op_sel_hi:[0,1,1]
	v_pk_fma_f32 v[30:31], v[252:253], v[40:41], v[28:29] op_sel_hi:[0,1,1]
	v_mul_f32_e32 v28, v33, v33
	v_mul_f32_e32 v29, v35, v35
	v_fmac_f32_e32 v28, v32, v32
	v_fmac_f32_e32 v29, v34, v34
	v_add_f32_e32 v28, v28, v29
	v_mul_f32_e32 v29, v31, v31
	v_fmac_f32_e32 v29, v30, v30
	v_add_f32_e32 v28, v29, v28
	v_mul_f32_e32 v29, v37, v37
	v_fmac_f32_e32 v29, v36, v36
	v_add_f32_e32 v44, v29, v28
	v_cvt_pk_bf16_f32 v28, v32, v33
	v_cvt_pk_bf16_f32 v29, v34, v35
	v_cvt_pk_bf16_f32 v30, v30, v31
	v_cvt_pk_bf16_f32 v31, v36, v37
	v_lshlrev_b32_e32 v36, 16, v232
	v_and_b32_e32 v37, 0xffff0000, v232
	v_lshlrev_b32_e32 v38, 16, v233
	v_and_b32_e32 v39, 0xffff0000, v233
	v_lshlrev_b32_e32 v42, 16, v235
	v_and_b32_e32 v43, 0xffff0000, v235
	v_pk_fma_f32 v[26:27], v[252:253], v[38:39], v[26:27] op_sel_hi:[0,1,1]
	v_pk_fma_f32 v[24:25], v[252:253], v[36:37], v[24:25] op_sel_hi:[0,1,1]
	v_lshlrev_b32_e32 v40, 16, v234
	v_and_b32_e32 v41, 0xffff0000, v234
	v_pk_fma_f32 v[36:37], v[252:253], v[42:43], v[22:23] op_sel_hi:[0,1,1]
	v_mul_f32_e32 v22, v25, v25
	v_mul_f32_e32 v23, v27, v27
	v_pk_fma_f32 v[20:21], v[252:253], v[40:41], v[20:21] op_sel_hi:[0,1,1]
	v_fmac_f32_e32 v22, v24, v24
	v_fmac_f32_e32 v23, v26, v26
	v_add_f32_e32 v22, v22, v23
	v_mul_f32_e32 v23, v21, v21
	v_fmac_f32_e32 v23, v20, v20
	v_add_f32_e32 v22, v23, v22
	v_mul_f32_e32 v23, v37, v37
	v_fmac_f32_e32 v23, v36, v36
	v_add_f32_e32 v22, v23, v22
	v_add_f32_e32 v38, v44, v22
	ds_bpermute_b32 v39, v116, v38
	v_lshlrev_b32_e32 v32, 7, v96
	v_and_b32_e32 v32, 0x7780, v32
	v_mov_b32_e32 v33, v1
	v_lshl_add_u64 v[34:35], v[2:3], 0, v[32:33]
	v_lshl_add_u64 v[34:35], v[34:35], 0, v[0:1]
	global_store_dwordx4 v[34:35], v[28:31], off
	v_cvt_pk_bf16_f32 v22, v24, v25
	v_cvt_pk_bf16_f32 v23, v26, v27
	v_cvt_pk_bf16_f32 v24, v20, v21
	s_waitcnt lgkmcnt(0)
	v_add_f32_e32 v20, v38, v39
	ds_bpermute_b32 v21, v117, v20
	v_lshl_add_u64 v[26:27], v[52:53], 0, v[32:33]
	v_lshl_add_u64 v[26:27], v[26:27], 0, v[0:1]
	v_cvt_pk_bf16_f32 v25, v36, v37
	global_store_dwordx4 v[26:27], v[22:25], off
	s_and_saveexec_b64 s[38:39], s[6:7]
	s_cbranch_execz .LBB0_500
	s_waitcnt lgkmcnt(0)
	v_add_f32_e32 v22, v20, v21
	s_lshl_b32 s40, s14, 2
	v_lshlrev_b64 v[20:21], 6, v[96:97]
	s_ashr_i32 s41, s40, 31
	v_lshl_add_u64 v[20:21], s[8:9], 0, v[20:21]
	v_lshl_add_u64 v[20:21], s[40:41], 2, v[20:21]
	s_lshl_b32 s16, s59, 2
	v_lshl_add_u64 v[20:21], v[20:21], 0, s[16:17]
	global_store_dword v[20:21], v22, off
.LBB0_500:
	s_or_b64 exec, exec, s[38:39]
	v_lshlrev_b32_e32 v20, 16, v236
	s_waitcnt lgkmcnt(0)
	v_and_b32_e32 v21, 0xffff0000, v236
	v_lshlrev_b32_e32 v22, 16, v237
	v_and_b32_e32 v23, 0xffff0000, v237
	v_lshlrev_b32_e32 v24, 16, v238
	v_and_b32_e32 v25, 0xffff0000, v238
	v_lshlrev_b32_e32 v26, 16, v239
	v_and_b32_e32 v27, 0xffff0000, v239
	v_pk_fma_f32 v[18:19], v[254:255], v[22:23], v[18:19] op_sel_hi:[0,1,1]
	v_pk_fma_f32 v[16:17], v[254:255], v[20:21], v[16:17] op_sel_hi:[0,1,1]
	v_pk_fma_f32 v[20:21], v[254:255], v[26:27], v[14:15] op_sel_hi:[0,1,1]
	v_pk_fma_f32 v[14:15], v[254:255], v[24:25], v[12:13] op_sel_hi:[0,1,1]
	v_mul_f32_e32 v12, v17, v17
	v_mul_f32_e32 v13, v19, v19
	v_fmac_f32_e32 v12, v16, v16
	v_fmac_f32_e32 v13, v18, v18
	v_add_f32_e32 v12, v12, v13
	v_mul_f32_e32 v13, v15, v15
	v_fmac_f32_e32 v13, v14, v14
	v_add_f32_e32 v12, v13, v12
	v_mul_f32_e32 v13, v21, v21
	v_fmac_f32_e32 v13, v20, v20
	v_add_f32_e32 v26, v13, v12
	v_cvt_pk_bf16_f32 v12, v16, v17
	v_cvt_pk_bf16_f32 v13, v18, v19
	v_cvt_pk_bf16_f32 v14, v14, v15
	v_cvt_pk_bf16_f32 v15, v20, v21
	v_lshlrev_b32_e32 v18, 16, v240
	v_and_b32_e32 v19, 0xffff0000, v240
	v_lshlrev_b32_e32 v20, 16, v241
	v_and_b32_e32 v21, 0xffff0000, v241
	v_lshlrev_b32_e32 v22, 16, v242
	v_and_b32_e32 v23, 0xffff0000, v242
	v_lshlrev_b32_e32 v24, 16, v243
	v_and_b32_e32 v25, 0xffff0000, v243
	v_pk_fma_f32 v[10:11], v[254:255], v[20:21], v[10:11] op_sel_hi:[0,1,1]
	v_pk_fma_f32 v[8:9], v[254:255], v[18:19], v[8:9] op_sel_hi:[0,1,1]
	v_pk_fma_f32 v[18:19], v[254:255], v[24:25], v[6:7] op_sel_hi:[0,1,1]
	v_pk_fma_f32 v[6:7], v[254:255], v[22:23], v[4:5] op_sel_hi:[0,1,1]
	v_mul_f32_e32 v4, v9, v9
	v_mul_f32_e32 v5, v11, v11
	v_fmac_f32_e32 v4, v8, v8
	v_fmac_f32_e32 v5, v10, v10
	v_add_f32_e32 v4, v4, v5
	v_mul_f32_e32 v5, v7, v7
	v_fmac_f32_e32 v5, v6, v6
	v_add_f32_e32 v4, v5, v4
	v_mul_f32_e32 v5, v19, v19
	v_fmac_f32_e32 v5, v18, v18
	v_add_f32_e32 v4, v5, v4
	v_add_f32_e32 v20, v26, v4
	ds_bpermute_b32 v21, v116, v20
	v_lshlrev_b32_e32 v16, 7, v92
	v_and_b32_e32 v16, 0x7f80, v16
	v_mov_b32_e32 v17, v1
	v_lshl_add_u64 v[2:3], v[2:3], 0, v[16:17]
	v_lshl_add_u64 v[2:3], v[2:3], 0, v[0:1]
	global_store_dwordx4 v[2:3], v[12:15], off
	s_waitcnt lgkmcnt(0)
	v_add_f32_e32 v2, v20, v21
	ds_bpermute_b32 v3, v117, v2
	v_cvt_pk_bf16_f32 v4, v8, v9
	v_lshl_add_u64 v[8:9], v[52:53], 0, v[16:17]
	v_lshl_add_u64 v[8:9], v[8:9], 0, v[0:1]
	v_cvt_pk_bf16_f32 v5, v10, v11
	v_cvt_pk_bf16_f32 v6, v6, v7
	v_cvt_pk_bf16_f32 v7, v18, v19
	global_store_dwordx4 v[8:9], v[4:7], off
	s_and_saveexec_b64 s[38:39], s[6:7]
	s_cbranch_execz .LBB0_502
	s_waitcnt lgkmcnt(0)
	v_add_f32_e32 v0, v2, v3
	s_lshl_b32 s14, s14, 2
	v_lshlrev_b64 v[2:3], 6, v[92:93]
	s_ashr_i32 s15, s14, 31
	v_lshl_add_u64 v[2:3], s[8:9], 0, v[2:3]
	v_lshl_add_u64 v[2:3], s[14:15], 2, v[2:3]
	s_lshl_b32 s16, s59, 2
	v_lshl_add_u64 v[2:3], v[2:3], 0, s[16:17]
	global_store_dword v[2:3], v0, off
